# attention D loop: running-max subtraction folded into QK MFMA C operand (32 fewer VALU per half tile)
# speedup vs baseline: 1.0088x; 1.0003x over previous
; #define MFMA32(a, b, c) __builtin_amdgcn_mfma_f32_32x32x16_bf16((a), (b), (c), 0, 0, 0)
; DI void attn_item(const Params& P, unsigned char* smem, bool samp, int b, int c) {
;     ...
;   const int h = wid;
;   bf16x8 qf[2][4];
;   for (int qh = 0; qh < 2; ++qh) {
;     int ql = qh * 32 + l32;
;     if (ql > nq - 1) ql = nq - 1;
;     const u16* p = (const u16*)(ws + R_QA) + (qrow0 + ql) * 512 + h * 64 + g * 8;
;     for (int ks = 0; ks < 4; ++ks) qf[qh][ks] = ld16(p + ks * 16);
;   }
;   f32x16 oacc[2][2];
;   for (int a = 0; a < 2; ++a) for (int q = 0; q < 2; ++q) for (int r = 0; r < 16; ++r) oacc[a][q][r] = 0.f;
;   float mrun[2] = {-1e30f, -1e30f}, lrun[2] = {0.f, 0.f};
;   const u16* kbase = Kb + (long)h * 2048 + lane * 8;
;   const u16* vbase = VTb + (long)h * 2048 + lane * 8;
;   bf16x8 kfN[4], vfN[2][2];
;   for (int ks = 0; ks < 4; ++ks) kfN[ks] = ld16(kbase + ks * 512);
;   for (int dh = 0; dh < 2; ++dh)
;     for (int s = 0; s < 2; ++s) vfN[dh][s] = ld16(vbase + (s * 2 + dh) * 512);
;   const int nhalf = ntiles * 2;
; #pragma unroll 1
;   for (int hh = 0; hh < nhalf; ++hh) {
;     const int kt = hh >> 1, kh = hh & 1;
;     const long key0 = (long)hh * 32;
;     const bool farT = (qpos0 - kt * 64) >= 1214;
;     f32x16 sacc[2];
;     __builtin_amdgcn_s_setprio(1);
;     for (int qh = 0; qh < 2; ++qh) {
;       f32x16 a = {};
;       for (int ks = 0; ks < 4; ++ks) a = MFMA32(kfN[ks], qf[qh][ks], a);
;       sacc[qh] = a;
;     }
;     __builtin_amdgcn_s_setprio(0);
;     if (hh + 1 < nhalf) {
;       const u16* kp = kbase + (long)(hh + 1) * 16384;
;       for (int ks = 0; ks < 4; ++ks) kfN[ks] = ld16(kp + ks * 512);
;     }
.LBB0_696:
	s_or_b64 exec, exec, s[2:3]
	v_readlane_b32 s0, v250, 2
	v_readlane_b32 s8, v250, 55
	v_readlane_b32 s1, v250, 3
	v_readlane_b32 s9, v250, 56
	s_load_dwordx2 s[96:97], s[0:1], 0xb8
	s_and_b64 s[0:1], s[8:9], exec
	v_readlane_b32 s0, v250, 54
	s_cselect_b32 s11, 0x1000, s0
	v_readlane_b32 s0, v250, 51
	v_readlane_b32 s1, v250, 42
	s_cselect_b32 s0, s1, s0
	s_mov_b32 s1, 0x2274a900
	s_cselect_b32 s12, s1, 0x1e74a900
	s_add_u32 s1, s86, s12
	s_addc_u32 s2, s87, 0
	s_lshl_b32 s90, s0, 1
	s_add_u32 s6, s1, s90
	s_addc_u32 s7, s2, 0
	s_and_b64 s[0:1], s[8:9], exec
	s_mov_b32 s0, 0xc080000
	s_cselect_b32 s13, s0, 0x8080000
	v_readlane_b32 s16, v250, 23
	v_readlane_b32 s17, v250, 24
	s_add_u32 s0, s16, s13
	s_addc_u32 s1, s17, 0
	s_add_u32 s8, s0, s90
	v_readlane_b32 s0, v250, 9
	s_addc_u32 s9, s1, 0
	s_add_i32 s2, s0, -1
	v_readlane_b32 s0, v250, 53
	s_andn2_b32 s0, s0, 63
	s_ashr_i32 s1, s0, 31
	s_lshl_b64 s[0:1], s[0:1], 1
	s_add_u32 s0, s86, s0
	s_addc_u32 s1, s87, s1
	v_readlane_b32 s14, v250, 57
	s_add_u32 s0, s0, 0x258a900
	v_min_u32_e32 v1, s2, v195
	s_mov_b32 s18, s14
	s_addc_u32 s1, s1, 0
	v_mov_b32_e32 v109, v3
	v_or_b32_e32 v1, s18, v1
	v_lshl_add_u64 v[4:5], s[0:1], 0, v[108:109]
	v_lshlrev_b32_e32 v2, 10, v1
	v_or_b32_e32 v1, 32, v195
	v_readlane_b32 s15, v250, 58
	v_lshl_add_u64 v[6:7], v[4:5], 0, v[2:3]
	v_min_u32_e32 v2, s2, v1
	v_readlane_b32 s2, v250, 14
	v_readlane_b32 s3, v250, 15
	s_mov_b32 s14, s2
	s_ashr_i32 s15, s2, 31
	s_lshl_b64 s[2:3], s[14:15], 12
	v_add_lshl_u32 v2, v2, s18, 10
	s_add_u32 s6, s6, s2
	v_lshl_add_u64 v[4:5], v[4:5], 0, v[2:3]
	s_addc_u32 s7, s7, s3
	v_lshlrev_b32_e32 v2, 4, v110
	s_waitcnt lgkmcnt(0)
	s_barrier
	global_load_dwordx4 v[114:117], v[6:7], off
	global_load_dwordx4 v[118:121], v[6:7], off offset:32
	global_load_dwordx4 v[122:125], v[6:7], off offset:64
	global_load_dwordx4 v[126:129], v[6:7], off offset:96
	global_load_dwordx4 v[130:133], v[4:5], off
	global_load_dwordx4 v[134:137], v[4:5], off offset:32
	global_load_dwordx4 v[138:141], v[4:5], off offset:64
	global_load_dwordx4 v[142:145], v[4:5], off offset:96
	v_lshl_add_u64 v[4:5], s[6:7], 0, v[2:3]
	s_add_u32 s6, s8, s2
	s_addc_u32 s7, s9, s3
	v_lshl_add_u64 v[6:7], s[6:7], 0, v[2:3]
	s_waitcnt vmcnt(0)
	global_load_dwordx4 v[146:149], v[6:7], off offset:3072
	global_load_dwordx4 v[158:161], v[6:7], off offset:2048
	global_load_dwordx4 v[154:157], v[6:7], off offset:1024
	global_load_dwordx4 v[150:153], v[6:7], off
	global_load_dwordx4 v[162:165], v[4:5], off offset:3072
	global_load_dwordx4 v[166:169], v[4:5], off offset:2048
	global_load_dwordx4 v[170:173], v[4:5], off offset:1024
	global_load_dwordx4 v[174:177], v[4:5], off
	s_lshl_b32 s9, s95, 1
	s_add_i32 s10, s11, 0xfffffb43
	s_add_u32 s6, s13, s2
	s_addc_u32 s7, 0, s3
	s_add_u32 s6, s16, s6
	s_addc_u32 s7, s17, s7
	v_and_b32_e32 v5, 64, v190
	s_add_u32 s2, s12, s2
	v_xor_b32_e32 v4, 32, v190
	v_add_u32_e32 v5, 64, v5
	s_addc_u32 s3, 0, s3
	v_cmp_lt_i32_e32 vcc, v4, v5
	s_add_u32 s2, s86, s2
	s_mulk_i32 s14, 0x1500
	v_cndmask_b32_e32 v4, v190, v4, vcc
	s_addc_u32 s3, s87, s3
	v_lshlrev_b32_e32 v198, 2, v178
	v_lshlrev_b32_e32 v196, 2, v4
	v_lshl_add_u64 v[178:179], s[6:7], 0, v[2:3]
	v_lshl_add_u64 v[180:181], s[2:3], 0, v[2:3]
	v_or_b32_e32 v2, s14, v108
	v_add_lshl_u32 v4, s11, v195, 2
	v_sub_u32_e32 v2, v2, v4
	v_readlane_b32 s2, v250, 26
	v_mov_b32_e32 v16, v3
	v_mov_b32_e32 v17, v3
	v_add_u32_e32 v199, s2, v2
	v_mov_b32_e32 v2, v3
	v_mov_b32_e32 v4, v3
	v_mov_b32_e32 v5, v3
	v_mov_b32_e32 v6, v3
	v_mov_b32_e32 v7, v3
	v_mov_b32_e32 v8, v3
	v_mov_b32_e32 v9, v3
	v_mov_b32_e32 v10, v3
	v_mov_b32_e32 v11, v3
	v_mov_b32_e32 v12, v3
	v_mov_b32_e32 v13, v3
	v_mov_b32_e32 v14, v3
	v_mov_b32_e32 v15, v3
	v_mov_b64_e32 v[32:33], v[16:17]
	v_mov_b64_e32 v[64:65], v[16:17]
	v_mov_b64_e32 v[48:49], v[16:17]
	s_waitcnt vmcnt(0)
	v_mov_b64_e32 v[80:81], v[16:17]
	v_readlane_b32 s28, v250, 33
	s_mov_b32 s8, 0
	s_mov_b32 s16, s18
	v_lshlrev_b32_e32 v200, 3, v195
	v_mov_b32_e32 v197, 0
	v_mov_b32_e32 v201, 0xf149f2ca
	v_mov_b64_e32 v[30:31], v[14:15]
	v_mov_b64_e32 v[28:29], v[12:13]
	v_mov_b64_e32 v[26:27], v[10:11]
	v_mov_b64_e32 v[24:25], v[8:9]
	v_mov_b64_e32 v[22:23], v[6:7]
	v_mov_b64_e32 v[20:21], v[4:5]
	v_mov_b64_e32 v[18:19], v[2:3]
	v_mov_b64_e32 v[62:63], v[14:15]
	v_mov_b64_e32 v[60:61], v[12:13]
	v_mov_b64_e32 v[58:59], v[10:11]
	v_mov_b64_e32 v[56:57], v[8:9]
	v_mov_b64_e32 v[54:55], v[6:7]
	v_mov_b64_e32 v[52:53], v[4:5]
	v_mov_b64_e32 v[50:51], v[2:3]
	v_mov_b64_e32 v[46:47], v[14:15]
	v_mov_b64_e32 v[44:45], v[12:13]
	v_mov_b64_e32 v[42:43], v[10:11]
	v_mov_b64_e32 v[40:41], v[8:9]
	v_mov_b64_e32 v[38:39], v[6:7]
	v_mov_b64_e32 v[36:37], v[4:5]
	v_mov_b64_e32 v[34:35], v[2:3]
	v_mov_b64_e32 v[78:79], v[14:15]
	v_mov_b64_e32 v[76:77], v[12:13]
	v_mov_b64_e32 v[74:75], v[10:11]
	v_mov_b64_e32 v[72:73], v[8:9]
	v_mov_b64_e32 v[70:71], v[6:7]
	v_mov_b64_e32 v[68:69], v[4:5]
	v_mov_b64_e32 v[66:67], v[2:3]
	v_mov_b32_e32 v2, 0xf149f2ca
	v_mov_b32_e32 v204, 0
	v_mov_b32_e32 v205, 0
	v_mov_b32_e32 v206, 0
	v_mov_b32_e32 v207, 0
	v_mov_b32_e32 v208, 0
	v_mov_b32_e32 v209, 0
	v_mov_b32_e32 v210, 0
	v_mov_b32_e32 v211, 0
	v_mov_b32_e32 v212, 0
	v_mov_b32_e32 v213, 0
	v_mov_b32_e32 v214, 0
	v_mov_b32_e32 v215, 0
	v_mov_b32_e32 v216, 0
	v_mov_b32_e32 v217, 0
	v_mov_b32_e32 v218, 0
	v_mov_b32_e32 v219, 0
	v_mov_b32_e32 v220, 0
	v_mov_b32_e32 v221, 0
	v_mov_b32_e32 v222, 0
	v_mov_b32_e32 v223, 0
	v_mov_b32_e32 v224, 0
	v_mov_b32_e32 v225, 0
	v_mov_b32_e32 v226, 0
	v_mov_b32_e32 v227, 0
	v_mov_b32_e32 v228, 0
	v_mov_b32_e32 v229, 0
	v_mov_b32_e32 v230, 0
	v_mov_b32_e32 v231, 0
	v_mov_b32_e32 v232, 0
	v_mov_b32_e32 v233, 0
	v_mov_b32_e32 v234, 0
	v_mov_b32_e32 v235, 0
	v_mov_b32_e32 v4, 0
	s_mov_b32 s2, 0
	v_readlane_b32 s29, v250, 34
.LBB0_697:
	s_setprio 1
	s_waitcnt vmcnt(4) lgkmcnt(0)
	v_mfma_f32_32x32x16_bf16 v[98:113], v[174:177], v[114:117], v[204:219]
	v_mfma_f32_32x32x16_bf16 v[82:97], v[174:177], v[130:133], v[220:235]
	v_mfma_f32_32x32x16_bf16 v[98:113], v[170:173], v[118:121], v[98:113]
	v_mfma_f32_32x32x16_bf16 v[82:97], v[170:173], v[134:137], v[82:97]
	v_mfma_f32_32x32x16_bf16 v[98:113], v[166:169], v[122:125], v[98:113]
	v_mfma_f32_32x32x16_bf16 v[82:97], v[166:169], v[138:141], v[82:97]
	v_mfma_f32_32x32x16_bf16 v[98:113], v[162:165], v[126:129], v[98:113]
	v_mfma_f32_32x32x16_bf16 v[82:97], v[162:165], v[142:145], v[82:97]
	s_setprio 0
	s_add_i32 s11, s2, 1
	s_cmp_lt_u32 s11, s9
	s_cselect_b64 s[6:7], -1, 0
	s_cselect_b32 s13, 0x8000, 0
	s_nop 0
	v_lshl_add_u64 v[6:7], v[180:181], 0, s[90:91]
	v_add_co_u32_e32 v6, vcc, s13, v6
	s_nop 1
	v_addc_co_u32_e32 v7, vcc, 0, v7, vcc
	global_load_dwordx4 v[174:177], v[6:7], off
	global_load_dwordx4 v[170:173], v[6:7], off offset:1024
	global_load_dwordx4 v[166:169], v[6:7], off offset:2048
	global_load_dwordx4 v[162:165], v[6:7], off offset:3072

; DI void attn_item(const Params& P, unsigned char* smem, bool samp, int b, int c) {
;     ...
;       const int mw = (int)(maskl[(kt * 64 + qh * 32 + l32) * 2 + kh] >> (4 * g));
;       const int relb = (int)key0 + 4 * g - (qpos0 + qh * 32 + l32) + T5OFF;
;       float mx = -1e30f;
;       if (!farT) {
;         for (int r = 0; r < 16; ++r) sacc[qh][r] += t5l[relb + (r & 3) + 8 * (r >> 2)];
;       }
;       for (int r = 0; r < 16; ++r) {
;         float l = sacc[qh][r];
;         const unsigned keep = (unsigned)__builtin_amdgcn_sbfe(mw, (r & 3) + 8 * (r >> 2), 1);
;         l = __uint_as_float((__float_as_uint(l) & keep) | (0xFF800000u & ~keep));
;         sacc[qh][r] = l;
;         mx = fmaxf(mx, l);
;       }
;       mx = fmaxf(mx, __shfl_xor(mx, 32));
;       if (__ballot(mx > mrun[qh]) != 0ull) {
;         const float mnew = fmaxf(mrun[qh], mx);
;         const float alpha = __builtin_amdgcn_exp2f(mrun[qh] - mnew);
;         mrun[qh] = mnew;
;         lrun[qh] *= alpha;
;         for (int dh = 0; dh < 2; ++dh)
;           for (int r = 0; r < 16; ++r) oacc[dh][qh][r] *= alpha;
;       }
.LBB0_701:
	s_waitcnt lgkmcnt(0)
	v_lshrrev_b32_e32 v202, v198, v5
	v_bfe_i32 v5, v202, 0, 1
	v_bfe_i32 v6, v202, 1, 1
	v_bitop3_b32 v5, v98, s93, v5 bitop3:0xe4
	v_bitop3_b32 v6, v99, s93, v6 bitop3:0xe4
	v_bfe_i32 v7, v202, 2, 1
	v_bfe_i32 v8, v202, 3, 1
	v_max3_f32 v9, v5, s4, v6
	v_bitop3_b32 v7, v100, s93, v7 bitop3:0xe4
	v_bitop3_b32 v8, v101, s93, v8 bitop3:0xe4
	v_max3_f32 v11, v9, v7, v8
	v_bfe_i32 v9, v202, 8, 1
	v_bfe_i32 v10, v202, 9, 1
	v_bitop3_b32 v9, v102, s93, v9 bitop3:0xe4
	v_bitop3_b32 v10, v103, s93, v10 bitop3:0xe4
	v_max3_f32 v13, v11, v9, v10
	v_bfe_i32 v11, v202, 10, 1
	v_bfe_i32 v12, v202, 11, 1
	v_bitop3_b32 v11, v104, s93, v11 bitop3:0xe4
	v_bitop3_b32 v12, v105, s93, v12 bitop3:0xe4
	v_max3_f32 v15, v13, v11, v12
	v_bfe_i32 v13, v202, 16, 1
	v_bfe_i32 v14, v202, 17, 1
	v_bitop3_b32 v13, v106, s93, v13 bitop3:0xe4
	v_bitop3_b32 v14, v107, s93, v14 bitop3:0xe4
	v_max3_f32 v17, v15, v13, v14
	v_bfe_i32 v15, v202, 18, 1
	v_bfe_i32 v16, v202, 19, 1
	v_bitop3_b32 v15, v108, s93, v15 bitop3:0xe4
	v_bitop3_b32 v16, v109, s93, v16 bitop3:0xe4
	v_max3_f32 v99, v17, v15, v16
	v_bfe_i32 v17, v202, 24, 1
	v_bfe_i32 v98, v202, 25, 1
	v_bitop3_b32 v17, v110, s93, v17 bitop3:0xe4
	v_bitop3_b32 v98, v111, s93, v98 bitop3:0xe4
	v_max3_f32 v101, v99, v17, v98
	v_bfe_i32 v99, v202, 26, 1
	v_bfe_i32 v100, v202, 27, 1
	v_bitop3_b32 v99, v112, s93, v99 bitop3:0xe4
	v_bitop3_b32 v100, v113, s93, v100 bitop3:0xe4
	v_max3_f32 v101, v101, v99, v100
	ds_bpermute_b32 v102, v196, v101
	s_waitcnt lgkmcnt(0)
	v_max_f32_e32 v102, v102, v102
	v_max_f32_e32 v101, v101, v102
	v_cmp_gt_f32_e32 vcc, v101, v2
	s_cbranch_vccz .LBB0_703
	v_max_f32_e32 v101, v101, v101
	v_max_f32_e32 v102, v2, v2
	v_max_f32_e32 v101, v102, v101
	v_sub_f32_e32 v2, v2, v101
	v_exp_f32_e32 v2, v2
	s_nop 0
	v_mul_f32_e32 v4, v4, v2
	v_pk_mul_f32 v[80:81], v[80:81], v[2:3] op_sel_hi:[1,0]
	v_pk_mul_f32 v[78:79], v[78:79], v[2:3] op_sel_hi:[1,0]
	v_pk_mul_f32 v[76:77], v[76:77], v[2:3] op_sel_hi:[1,0]
	v_pk_mul_f32 v[74:75], v[74:75], v[2:3] op_sel_hi:[1,0]
	v_pk_mul_f32 v[72:73], v[72:73], v[2:3] op_sel_hi:[1,0]
	v_pk_mul_f32 v[70:71], v[70:71], v[2:3] op_sel_hi:[1,0]
	v_pk_mul_f32 v[68:69], v[68:69], v[2:3] op_sel_hi:[1,0]
	v_pk_mul_f32 v[66:67], v[66:67], v[2:3] op_sel_hi:[1,0]
	v_pk_mul_f32 v[64:65], v[64:65], v[2:3] op_sel_hi:[1,0]
	v_pk_mul_f32 v[62:63], v[62:63], v[2:3] op_sel_hi:[1,0]
	v_pk_mul_f32 v[60:61], v[60:61], v[2:3] op_sel_hi:[1,0]
	v_pk_mul_f32 v[58:59], v[58:59], v[2:3] op_sel_hi:[1,0]
	v_pk_mul_f32 v[56:57], v[56:57], v[2:3] op_sel_hi:[1,0]
	v_pk_mul_f32 v[54:55], v[54:55], v[2:3] op_sel_hi:[1,0]
	v_pk_mul_f32 v[52:53], v[52:53], v[2:3] op_sel_hi:[1,0]
	v_pk_mul_f32 v[50:51], v[50:51], v[2:3] op_sel_hi:[1,0]
	v_cndmask_b32_e64 v2, v101, 0, vcc
	v_cndmask_b32_e64 v101, 0, v101, vcc
	v_sub_f32_e32 v5, v5, v101
	v_sub_f32_e32 v6, v6, v101
	v_sub_f32_e32 v7, v7, v101
	v_sub_f32_e32 v8, v8, v101
	v_sub_f32_e32 v9, v9, v101
	v_sub_f32_e32 v10, v10, v101
	v_sub_f32_e32 v11, v11, v101
	v_sub_f32_e32 v12, v12, v101
	v_sub_f32_e32 v13, v13, v101
	v_sub_f32_e32 v14, v14, v101
	v_sub_f32_e32 v15, v15, v101
	v_sub_f32_e32 v16, v16, v101
	v_sub_f32_e32 v17, v17, v101
	v_sub_f32_e32 v98, v98, v101
	v_sub_f32_e32 v99, v99, v101
	v_sub_f32_e32 v100, v100, v101
	v_sub_f32_e32 v204, v204, v101
	v_sub_f32_e32 v205, v205, v101
	v_sub_f32_e32 v206, v206, v101
	v_sub_f32_e32 v207, v207, v101
	v_sub_f32_e32 v208, v208, v101
	v_sub_f32_e32 v209, v209, v101
	v_sub_f32_e32 v210, v210, v101
	v_sub_f32_e32 v211, v211, v101
	v_sub_f32_e32 v212, v212, v101
	v_sub_f32_e32 v213, v213, v101
	v_sub_f32_e32 v214, v214, v101
	v_sub_f32_e32 v215, v215, v101
	v_sub_f32_e32 v216, v216, v101
	v_sub_f32_e32 v217, v217, v101
	v_sub_f32_e32 v218, v218, v101
	v_sub_f32_e32 v219, v219, v101

; #define MFMA32(a, b, c) __builtin_amdgcn_mfma_f32_32x32x16_bf16((a), (b), (c), 0, 0, 0)
; DI void attn_item(const Params& P, unsigned char* smem, bool samp, int b, int c) {
;     ...
;       const int mw = (int)(maskl[(kt * 64 + qh * 32 + l32) * 2 + kh] >> (4 * g));
;       const int relb = (int)key0 + 4 * g - (qpos0 + qh * 32 + l32) + T5OFF;
;       float mx = -1e30f;
;       if (!farT) {
;         for (int r = 0; r < 16; ++r) sacc[qh][r] += t5l[relb + (r & 3) + 8 * (r >> 2)];
;       }
;       for (int r = 0; r < 16; ++r) {
;         float l = sacc[qh][r];
;         const unsigned keep = (unsigned)__builtin_amdgcn_sbfe(mw, (r & 3) + 8 * (r >> 2), 1);
;         l = __uint_as_float((__float_as_uint(l) & keep) | (0xFF800000u & ~keep));
;         sacc[qh][r] = l;
;         mx = fmaxf(mx, l);
;       }
;       mx = fmaxf(mx, __shfl_xor(mx, 32));
;       if (__ballot(mx > mrun[qh]) != 0ull) {
;         const float mnew = fmaxf(mrun[qh], mx);
;         const float alpha = __builtin_amdgcn_exp2f(mrun[qh] - mnew);
;         mrun[qh] = mnew;
;         lrun[qh] *= alpha;
;         for (int dh = 0; dh < 2; ++dh)
;           for (int r = 0; r < 16; ++r) oacc[dh][qh][r] *= alpha;
;       }
;       const float mcur = mrun[qh];
;       float ps = 0.f;
;       for (int r = 0; r < 16; ++r) {
;         const float p = __builtin_amdgcn_exp2f(sacc[qh][r] - mcur);
;         sacc[qh][r] = p;
;         ps += p;
;       }
;       lrun[qh] += ps;
;     }
;     for (int qh = 0; qh < 2; ++qh)
;       for (int s = 0; s < 2; ++s) {
;         bf16x8 pf = packacc8(sacc[qh], s);
;         for (int dh = 0; dh < 2; ++dh) oacc[dh][qh] = MFMA32(vfN[dh][s], pf, oacc[dh][qh]);
.LBB0_705:
	s_waitcnt lgkmcnt(0)
	v_lshrrev_b32_e32 v110, v198, v101
	v_bfe_i32 v101, v110, 0, 1
	v_bitop3_b32 v109, v82, s93, v101 bitop3:0xe4
	v_bfe_i32 v82, v110, 1, 1
	v_bitop3_b32 v105, v83, s93, v82 bitop3:0xe4
	v_bfe_i32 v83, v110, 2, 1
	v_bitop3_b32 v106, v84, s93, v83 bitop3:0xe4
	v_bfe_i32 v83, v110, 3, 1
	v_bitop3_b32 v107, v85, s93, v83 bitop3:0xe4
	v_bfe_i32 v83, v110, 8, 1
	v_bitop3_b32 v108, v86, s93, v83 bitop3:0xe4
	v_bfe_i32 v83, v110, 9, 1
	v_bitop3_b32 v104, v87, s93, v83 bitop3:0xe4
	v_bfe_i32 v83, v110, 10, 1
	v_bitop3_b32 v101, v88, s93, v83 bitop3:0xe4
	v_bfe_i32 v83, v110, 11, 1
	v_max3_f32 v82, v109, s4, v105
	v_bitop3_b32 v102, v89, s93, v83 bitop3:0xe4
	v_bfe_i32 v83, v110, 16, 1
	v_max3_f32 v82, v82, v106, v107
	v_bitop3_b32 v103, v90, s93, v83 bitop3:0xe4
	v_bfe_i32 v83, v110, 17, 1
	v_max3_f32 v82, v82, v108, v104
	v_bitop3_b32 v91, v91, s93, v83 bitop3:0xe4
	v_bfe_i32 v83, v110, 18, 1
	v_max3_f32 v82, v82, v101, v102
	v_bitop3_b32 v87, v92, s93, v83 bitop3:0xe4
	v_bfe_i32 v83, v110, 19, 1
	v_max3_f32 v82, v82, v103, v91
	v_bitop3_b32 v83, v93, s93, v83 bitop3:0xe4
	v_bfe_i32 v84, v110, 24, 1
	v_bfe_i32 v85, v110, 25, 1
	v_max3_f32 v82, v82, v87, v83
	v_bitop3_b32 v84, v94, s93, v84 bitop3:0xe4
	v_bitop3_b32 v85, v95, s93, v85 bitop3:0xe4
	v_max3_f32 v88, v82, v84, v85
	v_bfe_i32 v82, v110, 26, 1
	v_bitop3_b32 v86, v96, s93, v82 bitop3:0xe4
	v_bfe_i32 v82, v110, 27, 1
	v_bitop3_b32 v82, v97, s93, v82 bitop3:0xe4
	v_max3_f32 v88, v88, v86, v82
	ds_bpermute_b32 v89, v196, v88
	s_waitcnt lgkmcnt(0)
	v_max_f32_e32 v89, v89, v89
	v_max_f32_e32 v88, v88, v89
	v_cmp_gt_f32_e32 vcc, v88, v201
	s_cbranch_vccz .LBB0_707
	v_max_f32_e32 v88, v88, v88
	v_max_f32_e32 v89, v201, v201
	v_max_f32_e32 v89, v89, v88
	v_sub_f32_e32 v88, v201, v89
	v_exp_f32_e32 v88, v88
	s_nop 0
	v_mul_f32_e32 v197, v197, v88
	v_pk_mul_f32 v[48:49], v[48:49], v[88:89] op_sel_hi:[1,0]
	v_pk_mul_f32 v[46:47], v[46:47], v[88:89] op_sel_hi:[1,0]
	v_pk_mul_f32 v[44:45], v[44:45], v[88:89] op_sel_hi:[1,0]
	v_pk_mul_f32 v[42:43], v[42:43], v[88:89] op_sel_hi:[1,0]
	v_pk_mul_f32 v[40:41], v[40:41], v[88:89] op_sel_hi:[1,0]
	v_pk_mul_f32 v[38:39], v[38:39], v[88:89] op_sel_hi:[1,0]
	v_pk_mul_f32 v[36:37], v[36:37], v[88:89] op_sel_hi:[1,0]
	v_pk_mul_f32 v[34:35], v[34:35], v[88:89] op_sel_hi:[1,0]
	v_pk_mul_f32 v[32:33], v[32:33], v[88:89] op_sel_hi:[1,0]
	v_pk_mul_f32 v[30:31], v[30:31], v[88:89] op_sel_hi:[1,0]
	v_pk_mul_f32 v[28:29], v[28:29], v[88:89] op_sel_hi:[1,0]
	v_pk_mul_f32 v[26:27], v[26:27], v[88:89] op_sel_hi:[1,0]
	v_pk_mul_f32 v[24:25], v[24:25], v[88:89] op_sel_hi:[1,0]
	v_pk_mul_f32 v[22:23], v[22:23], v[88:89] op_sel_hi:[1,0]
	v_pk_mul_f32 v[20:21], v[20:21], v[88:89] op_sel_hi:[1,0]
	v_pk_mul_f32 v[18:19], v[18:19], v[88:89] op_sel_hi:[1,0]
	v_cndmask_b32_e64 v201, v89, 0, vcc
	v_cndmask_b32_e64 v89, 0, v89, vcc
	v_sub_f32_e32 v109, v109, v89
	v_sub_f32_e32 v105, v105, v89
	v_sub_f32_e32 v106, v106, v89
	v_sub_f32_e32 v107, v107, v89
	v_sub_f32_e32 v108, v108, v89
	v_sub_f32_e32 v104, v104, v89
	v_sub_f32_e32 v101, v101, v89
	v_sub_f32_e32 v102, v102, v89
	v_sub_f32_e32 v103, v103, v89
	v_sub_f32_e32 v91, v91, v89
	v_sub_f32_e32 v87, v87, v89
	v_sub_f32_e32 v83, v83, v89
	v_sub_f32_e32 v84, v84, v89
	v_sub_f32_e32 v85, v85, v89
	v_sub_f32_e32 v86, v86, v89
	v_sub_f32_e32 v82, v82, v89
	v_sub_f32_e32 v220, v220, v89
	v_sub_f32_e32 v221, v221, v89
	v_sub_f32_e32 v222, v222, v89
	v_sub_f32_e32 v223, v223, v89
	v_sub_f32_e32 v224, v224, v89
	v_sub_f32_e32 v225, v225, v89
	v_sub_f32_e32 v226, v226, v89
	v_sub_f32_e32 v227, v227, v89
	v_sub_f32_e32 v228, v228, v89
	v_sub_f32_e32 v229, v229, v89
	v_sub_f32_e32 v230, v230, v89
	v_sub_f32_e32 v231, v231, v89
	v_sub_f32_e32 v232, v232, v89
	v_sub_f32_e32 v233, v233, v89
	v_sub_f32_e32 v234, v234, v89
	v_sub_f32_e32 v235, v235, v89
.LBB0_707:
	v_exp_f32_e32 v5, v5
	v_exp_f32_e32 v6, v6
	v_exp_f32_e32 v7, v7
	v_exp_f32_e32 v8, v8
	v_exp_f32_e32 v9, v9
	v_exp_f32_e32 v10, v10
	v_exp_f32_e32 v11, v11
	v_exp_f32_e32 v12, v12
	v_exp_f32_e32 v88, v98
	v_exp_f32_e32 v89, v99
	v_cvt_pk_bf16_f32 v96, v5, v6
	v_cvt_pk_bf16_f32 v97, v7, v8
	v_cvt_pk_bf16_f32 v98, v9, v10
	v_cvt_pk_bf16_f32 v99, v11, v12
	s_waitcnt vmcnt(4)
	s_nop 1
	v_mfma_f32_32x32x16_bf16 v[66:81], v[150:153], v[96:99], v[66:81]
	v_exp_f32_e32 v90, v100
	v_exp_f32_e32 v13, v13
	v_exp_f32_e32 v14, v14
	v_exp_f32_e32 v15, v15
	v_mfma_f32_32x32x16_bf16 v[50:65], v[154:157], v[96:99], v[50:65]
	v_exp_f32_e32 v16, v16
	v_exp_f32_e32 v17, v17
	v_exp_f32_e32 v92, v109
	v_exp_f32_e32 v93, v105
	v_exp_f32_e32 v94, v106
	v_exp_f32_e32 v95, v107
	v_exp_f32_e32 v96, v108
	v_exp_f32_e32 v97, v104
	v_exp_f32_e32 v98, v101
	v_exp_f32_e32 v99, v102
	v_cvt_pk_bf16_f32 v104, v13, v14
	v_cvt_pk_bf16_f32 v105, v15, v16
	v_cvt_pk_bf16_f32 v106, v17, v88
	v_cvt_pk_bf16_f32 v107, v89, v90
	v_exp_f32_e32 v100, v103
	v_cvt_pk_bf16_f32 v102, v92, v93
	v_mfma_f32_32x32x16_bf16 v[66:81], v[158:161], v[104:107], v[66:81]
	v_cvt_pk_bf16_f32 v103, v94, v95
	v_mfma_f32_32x32x16_bf16 v[50:65], v[146:149], v[104:107], v[50:65]
	v_cvt_pk_bf16_f32 v104, v96, v97
	v_cvt_pk_bf16_f32 v105, v98, v99
	v_exp_f32_e32 v91, v91
	v_exp_f32_e32 v87, v87
	v_exp_f32_e32 v83, v83
	v_mfma_f32_32x32x16_bf16 v[34:49], v[150:153], v[102:105], v[34:49]
	v_exp_f32_e32 v84, v84
	v_exp_f32_e32 v85, v85
	v_exp_f32_e32 v86, v86
	v_exp_f32_e32 v82, v82
	s_and_b32 s13, s6, 0x8000
	v_mfma_f32_32x32x16_bf16 v[18:33], v[154:157], v[102:105], v[18:33]
	v_cvt_pk_bf16_f32 v102, v100, v91
	v_cvt_pk_bf16_f32 v103, v87, v83
	v_cvt_pk_bf16_f32 v104, v84, v85
	v_cvt_pk_bf16_f32 v105, v86, v82
	s_nop 1
	v_mfma_f32_32x32x16_bf16 v[34:49], v[158:161], v[102:105], v[34:49]
	v_mfma_f32_32x32x16_bf16 v[18:33], v[146:149], v[102:105], v[18:33]
	s_nop 0
	v_lshl_add_u64 v[102:103], v[178:179], 0, s[90:91]
	v_add_co_u32_e32 v102, vcc, s13, v102
	s_nop 1
	v_addc_co_u32_e32 v103, vcc, 0, v103, vcc
	global_load_dwordx4 v[150:153], v[102:103], off
	global_load_dwordx4 v[154:157], v[102:103], off offset:1024
	global_load_dwordx4 v[158:161], v[102:103], off offset:2048
	global_load_dwordx4 v[146:149], v[102:103], off offset:3072
